# v37: v36 + cache-warming dummy loads: sgu unit issues the second LayerNorm batch's row loads (into unused registers) before the first batch; sample short-conv unit issues all 12 z loads up front
# baseline (speedup 1.0000x reference)
; __device__ __forceinline__ float bf2f(bf16 b) { return __uint_as_float(((unsigned)b) << 16); }
; __device__ __forceinline__ unsigned f2bf(float f) { unsigned u = __float_as_uint(f); return (u + 0x7fffu + ((u >> 16) & 1u)) >> 16; }
; #define SH_E(e) ((e) >= 0 ? bf2f(zc[(size_t)(e) * ZP + 1536]) * bf2f(zc[(size_t)(e) * ZP + 1792]) : (SAMPLE ? st[(2 + (e)) * GW] : 0.f))
; template <bool SAMPLE>
; __device__ __forceinline__ void short_unit(const bf16* __restrict__ Z, bf16* __restrict__ CAT, const float* __restrict__ state, float* __restrict__ news,
;                                            const float* __restrict__ sw, int seq, int t0, int nrows, int h, int lane) {
;     const int c = h * 64 + lane;
;     const size_t rowbase = SAMPLE ? (size_t)MP + (size_t)seq * ST : (size_t)seq * SEQ;
;     const bf16* zc = Z + rowbase * ZP + c;
;     const float* st = state + (size_t)seq * 2 * GW + c;
;     const float w0 = sw[c], w1 = sw[GW + c], w2 = sw[2 * GW + c];
;     ...
;     float e2 = SH_E(t0 - 2), e1 = SH_E(t0 - 1);
; #pragma unroll 4
;     for (int t = t0; t < t0 + nrows; ++t) {
;         const float e0 = SH_E(t); const float bg = bf2f(zc[(size_t)t * ZP + 1280]);
;         CAT[(rowbase + t) * DP + 768 + c] = (bf16)f2bf(bg * (w0 * e2 + w1 * e1 + w2 * e0));
;         e2 = e1; e1 = e0;
;     }
;     const int T = SAMPLE ? ST : SEQ;
;     if (t0 + nrows == T) { news[((size_t)seq * 2 + 0) * GW + c] = e2; news[((size_t)seq * 2 + 1) * GW + c] = e1; }
.LBB0_122:
	s_andn2_b64 vcc, exec, s[4:5]
	s_cbranch_vccnz .LBB0_124
	s_lshr_b32 s2, s6, 4
	v_mul_u32_u24_e32 v128, s2, v172
	s_lshl_b32 s2, s2, 6
	s_bitset1_b32 s2, 14
	s_waitcnt vmcnt(0)
	v_lshl_add_u64 v[0:1], s[62:63], 0, v[128:129]
	v_mul_hi_i32_i24_e32 v3, s2, v173
	v_mul_i32_i24_e32 v2, s2, v173
	v_mul_hi_i32_i24_e32 v5, s2, v174
	v_mul_i32_i24_e32 v4, s2, v174
	s_lshl_b32 s2, s6, 2
	v_lshl_add_u64 v[2:3], v[0:1], 0, v[2:3]
	v_lshl_add_u64 v[0:1], v[0:1], 0, v[4:5]
	s_mov_b64 s[4:5], 0x48000
	s_or_b32 s8, s2, 0x4000
	v_lshl_add_u64 v[10:11], v[0:1], 0, s[4:5]
	v_mad_u64_u32 v[2:3], s[4:5], s8, v175, v[2:3]
	v_lshl_add_u32 v0, s7, 6, v124
	s_lshl_b32 s2, s6, 11
	v_readlane_b32 s4, v252, 8
	v_ashrrev_i32_e32 v1, 31, v0
	s_add_u32 s4, s4, s2
	v_readlane_b32 s5, v252, 9
	v_lshlrev_b64 v[12:13], 1, v[0:1]
	s_addc_u32 s5, s5, 0
	v_lshlrev_b64 v[0:1], 2, v[0:1]
	v_lshl_add_u64 v[4:5], v[2:3], 0, v[12:13]
	v_lshl_add_u64 v[2:3], s[4:5], 0, v[0:1]
	v_lshl_add_u64 v[14:15], s[48:49], 0, v[0:1]
	global_load_dword v6, v[14:15], off
	global_load_dword v8, v[14:15], off offset:1024
	global_load_dword v7, v[14:15], off offset:2048
	global_load_dword v9, v[2:3], off
	s_nop 0
	global_load_dword v14, v[2:3], off offset:1024
	s_nop 0
	global_load_ushort v2, v[4:5], off offset:3072
	global_load_ushort v3, v[4:5], off offset:3584
	global_load_ushort v190, v[4:5], off offset:2560
	v_add_co_u32_e32 v200, vcc, s30, v4
	s_nop 1
	v_addc_co_u32_e32 v201, vcc, 0, v5, vcc
	global_load_ushort v191, v[200:201], off offset:3200
	global_load_ushort v192, v[200:201], off offset:3712
	global_load_ushort v193, v[200:201], off offset:2688
	v_add_co_u32_e32 v200, vcc, s21, v4
	s_nop 1
	v_addc_co_u32_e32 v201, vcc, 0, v5, vcc
	global_load_ushort v194, v[200:201], off offset:3328
	global_load_ushort v195, v[200:201], off offset:3840
	global_load_ushort v196, v[200:201], off offset:2816
	v_add_co_u32_e32 v200, vcc, s31, v4
	s_nop 1
	v_addc_co_u32_e32 v201, vcc, 0, v5, vcc
	global_load_ushort v197, v[200:201], off offset:3456
	global_load_ushort v198, v[200:201], off offset:3968
	global_load_ushort v199, v[200:201], off offset:2944
	s_lshl_b32 s84, s8, 11
	s_brev_b32 s4, 64
	s_waitcnt vmcnt(1)
	v_lshlrev_b32_e32 v2, 16, v2
	s_waitcnt vmcnt(0)
	v_lshlrev_b32_e32 v3, 16, v3
	v_mul_f32_e32 v15, v2, v3
	global_load_ushort v2, v[4:5], off offset:2560
	v_mul_f32_e32 v3, v8, v14
	v_fmac_f32_e32 v3, v6, v9
	v_fmac_f32_e32 v3, v7, v15
	s_waitcnt vmcnt(0)
	v_lshlrev_b32_e32 v2, 16, v2
	v_mul_f32_e32 v2, v3, v2
	v_bfe_u32 v3, v2, 16, 1
	v_add3_u32 v9, v2, v3, s90
	v_lshl_add_u64 v[2:3], v[10:11], 0, s[84:85]
	v_lshl_add_u64 v[2:3], v[2:3], 0, v[12:13]
	global_store_short_d16_hi v[2:3], v9, off offset:1536
	v_add_co_u32_e32 v2, vcc, s30, v4
	s_lshl_b32 s84, s6, 13
	s_nop 0
	v_addc_co_u32_e32 v3, vcc, 0, v5, vcc
	global_load_ushort v9, v[2:3], off offset:3200
	global_load_ushort v16, v[2:3], off offset:3712
	s_waitcnt vmcnt(1)
	v_lshlrev_b32_e32 v9, 16, v9
	global_load_ushort v2, v[2:3], off offset:2688
	s_waitcnt vmcnt(1)
	v_lshlrev_b32_e32 v16, 16, v16
	v_mul_f32_e32 v3, v8, v15
	v_mul_f32_e32 v9, v9, v16
	v_fmac_f32_e32 v3, v6, v14
	v_fmac_f32_e32 v3, v7, v9
	s_waitcnt vmcnt(0)
	v_lshlrev_b32_e32 v2, 16, v2
	v_mul_f32_e32 v2, v3, v2
	v_bfe_u32 v3, v2, 16, 1
	v_add3_u32 v14, v2, v3, s90
	v_lshl_add_u64 v[2:3], v[10:11], 0, s[84:85]
	v_lshl_add_u64 v[2:3], v[2:3], 0, v[12:13]
	v_add_co_u32_e32 v10, vcc, s4, v2
	s_mov_b32 s4, 0x2001000
	s_nop 0
	v_addc_co_u32_e32 v11, vcc, 0, v3, vcc
	global_store_short_d16_hi v[10:11], v14, off offset:3584
	v_add_co_u32_e32 v10, vcc, s21, v4
	s_nop 1
	v_addc_co_u32_e32 v11, vcc, 0, v5, vcc
	global_load_ushort v12, v[10:11], off offset:3328
	global_load_ushort v13, v[10:11], off offset:3840
	v_add_co_u32_e32 v2, vcc, s4, v2
	global_load_ushort v10, v[10:11], off offset:2816
	v_mul_f32_e32 v11, v8, v9
	v_fmac_f32_e32 v11, v6, v15
	v_addc_co_u32_e32 v3, vcc, 0, v3, vcc
	v_add_co_u32_e32 v4, vcc, s31, v4
	v_readlane_b32 s4, v252, 10
	s_nop 0
	v_addc_co_u32_e32 v5, vcc, 0, v5, vcc
	s_add_u32 s4, s4, s2
	v_readlane_b32 s2, v252, 11
	s_addc_u32 s5, s2, 0
	v_lshl_add_u64 v[0:1], s[4:5], 0, v[0:1]
	s_waitcnt vmcnt(2)
	v_lshlrev_b32_e32 v12, 16, v12
	s_waitcnt vmcnt(1)
	v_lshlrev_b32_e32 v13, 16, v13
	v_mul_f32_e32 v12, v12, v13
	v_fmac_f32_e32 v11, v7, v12
	s_waitcnt vmcnt(0)
	v_lshlrev_b32_e32 v10, 16, v10
	v_mul_f32_e32 v10, v11, v10
	v_bfe_u32 v11, v10, 16, 1
	v_add3_u32 v10, v10, v11, s90
	global_store_short_d16_hi v[2:3], v10, off offset:1536
	global_load_ushort v10, v[4:5], off offset:3456
	s_nop 0
	global_load_ushort v11, v[4:5], off offset:3968
	s_waitcnt vmcnt(1)
	v_lshlrev_b32_e32 v10, 16, v10
	global_load_ushort v4, v[4:5], off offset:2944
	s_waitcnt vmcnt(1)
	v_lshlrev_b32_e32 v11, 16, v11
	v_mul_f32_e32 v5, v8, v12
	v_mul_f32_e32 v10, v10, v11
	v_fmac_f32_e32 v5, v6, v9
	v_fmac_f32_e32 v5, v7, v10
	s_waitcnt vmcnt(0)
	v_lshlrev_b32_e32 v4, 16, v4
	v_mul_f32_e32 v4, v5, v4
	v_bfe_u32 v5, v4, 16, 1
	v_add3_u32 v4, v4, v5, s90
	global_store_short_d16_hi v[2:3], v4, off offset:3584
	global_store_dword v[0:1], v12, off
	global_store_dword v[0:1], v10, off offset:1024

; __device__ __forceinline__ void sgu_unit(const bf16* __restrict__ Z, bf16* __restrict__ CAT, const bf16* __restrict__ Wb, const float* __restrict__ lg, const float* __restrict__ lb,
;                                          const float* __restrict__ sb, int chunk, int h, LAS bf16* vT, int lane) {
;     const size_t r0 = (size_t)chunk * 128;
;     const int fr = lane & 15, fq = lane >> 4;
;     bf16x8 wf[8][4];
; #pragma unroll
;     for (int mt = 0; mt < 8; ++mt)
; #pragma unroll
;         for (int ks = 0; ks < 4; ++ks) if (ks * 32 <= mt * 16 + 15) wf[mt][ks] = *(const bf16x8*)(Wb + ((size_t)(h * 128 + mt * 16 + fr) * 128 + ks * 32 + fq * 8));
;     { const int rr = lane >> 3, cg = lane & 7, c0 = h * 64 + cg * 8;
;       float gg[8], bb[8];
; #pragma unroll
;       for (int i = 0; i < 8; ++i) { gg[i] = lg[c0 + i]; bb[i] = lb[c0 + i]; }
; #pragma unroll 1
;       for (int jh = 0; jh < 16; jh += 8) {
;           v4u raw[8];
; #pragma unroll
;           for (int j = 0; j < 8; ++j) raw[j] = ld16(Z + (r0 + 8 * (jh + j) + rr) * ZP + 1024 + c0);
.LBB0_413:
	s_andn2_b64 vcc, exec, s[4:5]
	s_cbranch_vccnz .LBB0_417
	s_ashr_i32 s12, s87, 6
	s_ashr_i32 s13, s12, 31
	s_mul_i32 s4, s12, 0x1040000
	s_mul_hi_i32 s2, s12, 0x1040000
	s_add_u32 s4, s64, s4
	s_addc_u32 s5, s65, s2
	s_mul_i32 s6, s12, 0xff7c0000
	s_mul_hi_i32 s2, s12, 0xff7c0000
	s_add_u32 s10, s4, s6
	s_addc_u32 s11, s5, s2
	s_and_b32 s2, s87, 3
	v_ashrrev_i32_e32 v157, 4, v124
	v_and_b32_e32 v156, 15, v124
	s_lshl_b32 s16, s2, 7
	s_nop 0
	v_lshlrev_b32_e32 v0, 3, v157
	v_or_b32_e32 v158, s16, v156
	v_ashrrev_i32_e32 v1, 31, v0
	v_lshl_add_u64 v[0:1], v[0:1], 1, s[40:41]
	v_lshlrev_b32_e32 v128, 8, v158
	v_lshl_add_u64 v[0:1], v[0:1], 0, v[128:129]
	v_add_co_u32_e32 v2, vcc, s21, v0
	v_lshlrev_b32_e32 v98, 3, v124
	s_nop 0
	v_addc_co_u32_e32 v3, vcc, 0, v1, vcc
	v_add_co_u32_e32 v4, vcc, s31, v0
	global_load_dwordx4 v[72:75], v[2:3], off offset:-4096
	global_load_dwordx4 v[68:71], v[2:3], off
	v_addc_co_u32_e32 v5, vcc, 0, v1, vcc
	v_add_co_u32_e32 v6, vcc, s28, v0
	s_lshl_b32 s17, s2, 6
	s_nop 0
	v_addc_co_u32_e32 v7, vcc, 0, v1, vcc
	global_load_dwordx4 v[64:67], v[2:3], off offset:64
	global_load_dwordx4 v[60:63], v[6:7], off offset:-4096
	global_load_dwordx4 v[76:79], v[0:1], off
	global_load_dwordx4 v[56:59], v[4:5], off offset:64
	global_load_dwordx4 v[52:55], v[6:7], off
	global_load_dwordx4 v[48:51], v[6:7], off offset:64
	v_add_co_u32_e32 v2, vcc, s36, v0
	v_and_b32_e32 v99, 56, v98
	s_nop 0
	v_addc_co_u32_e32 v3, vcc, 0, v1, vcc
	v_add_co_u32_e32 v4, vcc, s29, v0
	v_or_b32_e32 v100, s17, v99
	s_nop 0
	v_addc_co_u32_e32 v5, vcc, 0, v1, vcc
	global_load_dwordx4 v[44:47], v[6:7], off offset:128
	global_load_dwordx4 v[40:43], v[4:5], off offset:-4096
	global_load_dwordx4 v[36:39], v[2:3], off offset:64
	global_load_dwordx4 v[32:35], v[2:3], off offset:128
	global_load_dwordx4 v[28:31], v[4:5], off
	global_load_dwordx4 v[24:27], v[4:5], off offset:64
	global_load_dwordx4 v[20:23], v[4:5], off offset:128
	global_load_dwordx4 v[16:19], v[4:5], off offset:192
	v_add_co_u32_e32 v0, vcc, s37, v0
	v_lshlrev_b32_e32 v92, 2, v100
	s_nop 0
	v_addc_co_u32_e32 v1, vcc, 0, v1, vcc
	global_load_dwordx4 v[12:15], v[0:1], off
	global_load_dwordx4 v[8:11], v[0:1], off offset:64
	global_load_dwordx4 v[4:7], v[0:1], off offset:128
	s_nop 0
	global_load_dwordx4 v[0:3], v[0:1], off offset:192
	s_nop 0
	global_load_dwordx4 v[80:83], v92, s[50:51]
	global_load_dwordx4 v[84:87], v92, s[50:51] offset:16
	global_load_dwordx4 v[88:91], v92, s[0:1]
	s_nop 0
	global_load_dwordx4 v[92:95], v92, s[0:1] offset:16
	s_ashr_i32 s6, s87, 2
	s_ashr_i32 s7, s6, 31
	v_ashrrev_i32_e32 v96, 3, v124
	s_lshl_b64 s[8:9], s[6:7], 7
	v_ashrrev_i32_e32 v97, 31, v96
	v_lshl_add_u64 v[124:125], s[8:9], 0, v[96:97]
	v_lshlrev_b32_e32 v97, 8, v99
	v_lshlrev_b32_e32 v96, 1, v96
	v_add3_u32 v161, s69, v97, v96
	v_or_b32_e32 v97, 1, v99
	v_lshlrev_b32_e32 v97, 8, v97
	v_add3_u32 v163, s69, v97, v96
	v_or_b32_e32 v97, 2, v99
	v_lshlrev_b32_e32 v97, 8, v97
	v_add3_u32 v165, s69, v97, v96
	v_or_b32_e32 v97, 3, v99
	v_lshlrev_b32_e32 v97, 8, v97
	v_add3_u32 v167, s69, v97, v96
	v_or_b32_e32 v97, 4, v99
	v_lshlrev_b32_e32 v97, 8, v97
	v_add3_u32 v188, s69, v97, v96
	v_or_b32_e32 v97, 5, v99
	v_lshlrev_b32_e32 v97, 8, v97
	v_add3_u32 v190, s69, v97, v96
	v_or_b32_e32 v97, 6, v99
	v_lshlrev_b32_e32 v97, 8, v97
	v_add3_u32 v192, s69, v97, v96
	v_or_b32_e32 v97, 7, v99
	v_lshlrev_b32_e32 v97, 8, v97
	v_lshlrev_b32_e32 v128, 1, v100
	s_mov_b32 s18, 0
	v_bfe_u32 v159, v98, 4, 2
	v_and_b32_e32 v160, 8, v98
	v_bitop3_b32 v162, v99, 9, 1 bitop3:0xc8
	v_bitop3_b32 v164, v99, 10, 2 bitop3:0xc8
	v_bitop3_b32 v166, v99, 11, 3 bitop3:0xc8
	v_bitop3_b32 v187, v99, 12, 4 bitop3:0xc8
	v_bitop3_b32 v189, v99, 13, 5 bitop3:0xc8
	v_bitop3_b32 v191, v99, 14, 6 bitop3:0xc8
	v_bitop3_b32 v193, v99, 15, 7 bitop3:0xc8
	v_add3_u32 v194, s69, v97, v96
	v_lshl_add_u64 v[126:127], s[10:11], 0, v[128:129]
	s_mov_b64 s[14:15], -1
	s_movk_i32 s6, 64
	s_mov_b32 s7, 0
	v_lshl_add_u64 v[244:245], v[124:125], 0, s[6:7]
	v_mad_u64_u32 v[246:247], vcc, v244, s78, v[126:127]
	v_mad_i32_i24 v247, v245, s78, v247
	global_load_dwordx4 v[212:215], v[246:247], off offset:2048
	s_movk_i32 s6, 72
	s_mov_b32 s7, 0
	v_lshl_add_u64 v[244:245], v[124:125], 0, s[6:7]
	v_mad_u64_u32 v[246:247], vcc, v244, s78, v[126:127]
	v_mad_i32_i24 v247, v245, s78, v247
	global_load_dwordx4 v[216:219], v[246:247], off offset:2048
	s_movk_i32 s6, 80
	s_mov_b32 s7, 0
	v_lshl_add_u64 v[244:245], v[124:125], 0, s[6:7]
	v_mad_u64_u32 v[246:247], vcc, v244, s78, v[126:127]
	v_mad_i32_i24 v247, v245, s78, v247
	global_load_dwordx4 v[220:223], v[246:247], off offset:2048
	s_movk_i32 s6, 88
	s_mov_b32 s7, 0
	v_lshl_add_u64 v[244:245], v[124:125], 0, s[6:7]
	v_mad_u64_u32 v[246:247], vcc, v244, s78, v[126:127]
	v_mad_i32_i24 v247, v245, s78, v247
	global_load_dwordx4 v[224:227], v[246:247], off offset:2048
	s_movk_i32 s6, 96
	s_mov_b32 s7, 0
	v_lshl_add_u64 v[244:245], v[124:125], 0, s[6:7]
	v_mad_u64_u32 v[246:247], vcc, v244, s78, v[126:127]
	v_mad_i32_i24 v247, v245, s78, v247
	global_load_dwordx4 v[228:231], v[246:247], off offset:2048
	s_movk_i32 s6, 104
	s_mov_b32 s7, 0
	v_lshl_add_u64 v[244:245], v[124:125], 0, s[6:7]
	v_mad_u64_u32 v[246:247], vcc, v244, s78, v[126:127]
	v_mad_i32_i24 v247, v245, s78, v247
	global_load_dwordx4 v[232:235], v[246:247], off offset:2048
	s_movk_i32 s6, 112
	s_mov_b32 s7, 0
	v_lshl_add_u64 v[244:245], v[124:125], 0, s[6:7]
	v_mad_u64_u32 v[246:247], vcc, v244, s78, v[126:127]
	v_mad_i32_i24 v247, v245, s78, v247
	global_load_dwordx4 v[236:239], v[246:247], off offset:2048
	s_movk_i32 s6, 120
	s_mov_b32 s7, 0
	v_lshl_add_u64 v[244:245], v[124:125], 0, s[6:7]
	v_mad_u64_u32 v[246:247], vcc, v244, s78, v[126:127]
	v_mad_i32_i24 v247, v245, s78, v247
	global_load_dwordx4 v[240:243], v[246:247], off offset:2048
